# XCD-local seams: P5|P6|P7|P8|P9|P1 chain synchronises within the XCD only (norm_rows rows remapped to the XCD's own GEMM tiles; placement census with fallback to full barriers)
# speedup vs baseline: 1.0084x; 1.0084x over previous
; #define LAS __attribute__((address_space(3)))
; __device__ __forceinline__ unsigned xb_add(unsigned* p, unsigned v) { return __hip_atomic_fetch_add(p, v, __ATOMIC_RELAXED, __HIP_MEMORY_SCOPE_AGENT); }
; __device__ __forceinline__ unsigned xb_xcc_id() { return (unsigned)__builtin_amdgcn_s_getreg((3 << 11) | 20) & 0xFu; }
; __device__ __forceinline__ XcdBarrier xcd_barrier_post(unsigned* bar, volatile LAS unsigned* st) {
;     XcdBarrier b; b.bar = bar; b.x = xb_xcc_id(); b.st = st;
;     if (threadIdx.x == 0) (void)xb_add(&bar[XB_XCNT(b.x)], 1u);
;     return b;
; __global__ void __launch_bounds__(NTHR, 2) fwd(Args args) {
;     ...
;     const int lo = args.ph_lo, hi = args.ph_hi;
;     if (threadIdx.x < 64) MISC[threadIdx.x] = 0;
;     __syncthreads();
;     XcdBarrier bar = xcd_barrier_post(ctl + CW_BAR, (volatile LAS unsigned*)(MISC + 8));
_Z3fwd4Args:
	s_mov_b32 s100, 0
	s_mov_b32 s98, 0
	s_mov_b32 s99, 0
	s_load_dwordx2 s[58:59], s[0:1], 0xb0
	s_load_dword s3, s[0:1], 0xb8
	s_add_u32 s4, s0, 0xb8
	s_addc_u32 s5, s1, 0
	v_and_b32_e32 v232, 0x3ff, v0
	v_writelane_b32 v254, s4, 0
	v_cmp_gt_u32_e32 vcc, 64, v232
	s_nop 0
	v_writelane_b32 v254, s5, 1
	s_and_saveexec_b64 s[4:5], vcc
	v_lshl_add_u32 v1, v232, 2, 0
	v_add_u32_e32 v1, 0x22000, v1
	v_mov_b32_e32 v2, 0
	ds_write_b32 v1, v2
	s_or_b64 exec, exec, s[4:5]
	s_mov_b32 s4, 21
	s_waitcnt lgkmcnt(0)
	s_barrier
	s_ashr_i32 s5, s4, 31
	s_lshl_b64 s[4:5], s[4:5], 3
	s_add_u32 s4, s0, s4
	s_addc_u32 s5, s1, s5
	s_load_dwordx2 s[8:9], s[4:5], 0x0
	s_getreg_b32 s4, hwreg(HW_REG_XCC_ID, 0, 4)
	v_cmp_eq_u32_e64 s[74:75], 0, v232
	s_waitcnt lgkmcnt(0)
	s_add_u32 s10, s8, 0x8000
	s_addc_u32 s11, s9, 0
	s_and_b32 s52, s4, 15
	s_and_saveexec_b64 s[4:5], s[74:75]
	s_cbranch_execz .LBB0_5
	s_mov_b64 s[6:7], exec
	v_mbcnt_lo_u32_b32 v1, s6, 0
	v_mbcnt_hi_u32_b32 v1, s7, v1
	v_cmp_eq_u32_e32 vcc, 0, v1
	s_and_b64 s[12:13], exec, vcc
	s_mov_b64 exec, s[12:13]
	s_cbranch_execz .LBB0_5
	s_lshl_b32 s12, s52, 8
	s_bcnt1_i32_b64 s6, s[6:7]
	v_mov_b32_e32 v1, s12
	v_mov_b32_e32 v2, s6
	global_atomic_add v1, v2, s[10:11] offset:1024
	s_and_b32 s12, s2, 7
	s_lshl_b32 s12, s12, 6
	s_addk_i32 s12, 0x3800
	s_lshl_b32 s13, 1, s52
	v_mov_b32_e32 v3, s12
	v_mov_b32_e32 v4, s13
	global_atomic_or v3, v4, s[10:11]

; __device__ __forceinline__ unsigned xb_ld(unsigned* p)              { return __hip_atomic_load(p, __ATOMIC_RELAXED, __HIP_MEMORY_SCOPE_AGENT); }
; __device__ __forceinline__ unsigned xb_add(unsigned* p, unsigned v) { return __hip_atomic_fetch_add(p, v, __ATOMIC_RELAXED, __HIP_MEMORY_SCOPE_AGENT); }
; #define XB_SPIN(cond, bar) do { unsigned _sp = 0; while (cond) { __builtin_amdgcn_s_sleep(1); \
;     if ((++_sp & 255u) == 0u) { if (xb_ld(&(bar)[XB_TMO])) break; if (_sp > XB_SPIN_CAP) { atomicAdd(&(bar)[XB_TMO], 1u); break; } } } } while (0)
; __device__ __forceinline__ void xcd_barrier(const XcdBarrier& b) {
;     ...
;         const unsigned old = xb_add(&bar[XB_XSUB(b.x)], 1u);
;         const unsigned gen = old / nloc;
;         if (old + 1u == (gen + 1u) * nloc) {
;             __builtin_amdgcn_fence(__ATOMIC_RELEASE, "agent");
;             asm volatile("s_waitcnt vmcnt(0)" ::: "memory");
;             const unsigned og = xb_add(&bar[XB_TOP], 1u);
;             const unsigned tg = og / nx;
;             if (og + 1u == (tg + 1u) * nx) xb_add(&bar[XB_TOPGEN], 1u);
;             else XB_SPIN(xb_ld(&bar[XB_TOPGEN]) == tg, bar);
;             __builtin_amdgcn_fence(__ATOMIC_ACQUIRE, "agent");
;             xb_add(&bar[XB_XGEN(b.x)], 1u);
.LBB0_611:
	s_andn2_saveexec_b64 s[22:23], s[34:35]
	s_cbranch_execz .LBB0_631
	s_mov_b64 s[34:35], exec
	s_cmp_lg_u32 s100, 0
	s_cbranch_scc1 .Llseam_known_17051
	v_readlane_b32 s22, v255, 6
	v_readlane_b32 s23, v255, 7
	s_nop 4
	global_load_dword v6, v1, s[22:23] offset:1024 sc1
	global_load_dword v7, v1, s[22:23] offset:1088 sc1
	global_load_dword v8, v1, s[22:23] offset:1152 sc1
	global_load_dword v9, v1, s[22:23] offset:1216 sc1
	global_load_dword v10, v1, s[22:23] offset:1280 sc1
	global_load_dword v11, v1, s[22:23] offset:1344 sc1
	global_load_dword v12, v1, s[22:23] offset:1408 sc1
	global_load_dword v13, v1, s[22:23] offset:1472 sc1
	s_waitcnt vmcnt(0)
	v_add_u32_e32 v14, -1, v6
	v_and_b32_e32 v14, v14, v6
	v_add_u32_e32 v15, -1, v7
	v_and_b32_e32 v15, v15, v7
	v_or_b32_e32 v14, v14, v15
	v_add_u32_e32 v15, -1, v8
	v_and_b32_e32 v15, v15, v8
	v_or_b32_e32 v14, v14, v15
	v_add_u32_e32 v15, -1, v9
	v_and_b32_e32 v15, v15, v9
	v_or_b32_e32 v14, v14, v15
	v_add_u32_e32 v15, -1, v10
	v_and_b32_e32 v15, v15, v10
	v_or_b32_e32 v14, v14, v15
	v_add_u32_e32 v15, -1, v11
	v_and_b32_e32 v15, v15, v11
	v_or_b32_e32 v14, v14, v15
	v_add_u32_e32 v15, -1, v12
	v_and_b32_e32 v15, v15, v12
	v_or_b32_e32 v14, v14, v15
	v_add_u32_e32 v15, -1, v13
	v_and_b32_e32 v15, v15, v13
	v_or_b32_e32 v14, v14, v15
	s_nop 0
	v_readfirstlane_b32 s22, v14
	s_cmp_eq_u32 s22, 0
	s_cselect_b32 s100, 1, 2
.Llseam_known_17051:
	s_cmp_eq_u32 s100, 1
	s_cbranch_scc1 .LBB0_628
	buffer_wbl2 sc1
	s_waitcnt lgkmcnt(0)
	s_waitcnt vmcnt(0)
	v_mbcnt_lo_u32_b32 v0, s34, 0
	v_mbcnt_hi_u32_b32 v0, s35, v0
	v_cmp_eq_u32_e32 vcc, 0, v0
	s_and_saveexec_b64 s[36:37], vcc
	s_cbranch_execz .LBB0_614
	s_bcnt1_i32_b64 s22, s[34:35]
	v_mov_b32_e32 v3, s22
	v_readlane_b32 s22, v255, 6
	v_readlane_b32 s23, v255, 7
	s_nop 4
	global_atomic_add v3, v1, v3, s[22:23] sc0

; __device__ __forceinline__ const float* karg(int k) { int kk = k; asm volatile("" : "+s"(kk)); return ((const float* const __attribute__((address_space(4)))*)__builtin_amdgcn_kernarg_segment_ptr())[kk]; }
; template <bool FINAL, bool DUMMY = false> __device__ __forceinline__ void norm_rows(const bfu* F, bfu* XB, const float* g1, float* RS, float* xout, int gw, int NGW, int lane, bfu* dummy = nullptr) {
;     int m = gw; if (m >= M) return;
;     v4u fw[4], xw[4];
; #pragma unroll
;     for (int j = 0; j < 4; ++j) { fw[j] = __builtin_nontemporal_load((const v4u*)(F + (size_t)m * DM) + lane + 64 * j); xw[j] = ((const v4u*)(XB + (size_t)m * DM) + lane)[64 * j]; }
;     for (; m < M; m += NGW) {
;         f32x4 f[8], x[8]; float s = 0.f;
; #pragma unroll
;         for (int j = 0; j < 4; ++j) {
;             f[2 * j] = (f32x4){bflo(fw[j].x), bfhi(fw[j].x), bflo(fw[j].y), bfhi(fw[j].y)}; f[2 * j + 1] = (f32x4){bflo(fw[j].z), bfhi(fw[j].z), bflo(fw[j].w), bfhi(fw[j].w)};
;             x[2 * j] = (f32x4){bflo(xw[j].x), bfhi(xw[j].x), bflo(xw[j].y), bfhi(xw[j].y)}; x[2 * j + 1] = (f32x4){bflo(xw[j].z), bfhi(xw[j].z), bflo(xw[j].w), bfhi(xw[j].w)}; }
;         const int mn = m + NGW;
;         if (mn < M) {
; #pragma unroll
;             for (int j = 0; j < 4; ++j) { fw[j] = __builtin_nontemporal_load((const v4u*)(F + (size_t)mn * DM) + lane + 64 * j); xw[j] = ((const v4u*)(XB + (size_t)mn * DM) + lane)[64 * j]; }
;         }
; #pragma unroll
;         for (int k = 0; k < 8; ++k) s += (f[k].x * f[k].x + f[k].y * f[k].y) + (f[k].z * f[k].z + f[k].w * f[k].w);
;         const float rstd1 = 1.f / sqrtf(wave_sum(s) * (1.f / DM) + EPS);
;         float s2 = 0.f;
; #pragma unroll
;         for (int k = 0; k < 8; ++k) { const f32x4 gg = ((const f32x4*)g1)[2 * lane + 128 * (k >> 1) + (k & 1)]; x[k] = x[k] + f[k] * rstd1 * gg; s2 += (x[k].x * x[k].x + x[k].y * x[k].y) + (x[k].z * x[k].z + x[k].w * x[k].w); }
; __global__ void __launch_bounds__(NTHR, 2) fwd(Args args) {
;     ...
;         if (XEN(6) && IN_PH()) for (int rep = 0; rep < XREP(6); ++rep) { PIN_TID(); if (XREP(6) > 1 && rep == 0) norm_rows<false, true>(F32, XN, karg(14) + l * DM, RS, nullptr, gw, NGW, lane, PROJ); else norm_rows<false>(F32, XN, karg(14) + l * DM, RS, nullptr, gw, NGW, lane); }
.LBB0_632:
	s_cmp_le_i32 s58, s20
	s_cselect_b64 s[4:5], -1, 0
	s_and_b64 s[22:23], s[4:5], s[26:27]
	s_andn2_b64 vcc, exec, s[22:23]
	s_cbranch_vccnz .LBB0_640
	v_mov_b32_e32 v0, v232
	s_mov_b32 s42, 21
	v_readfirstlane_b32 s20, v0
	s_ashr_i32 s22, s20, 6
	s_and_b32 s20, s2, 7
	s_lshl_b32 s20, s20, 11
	s_lshr_b32 s27, s2, 3
	s_lshl_b32 s27, s27, 3
	s_add_i32 s20, s20, s27
	s_add_i32 s26, s22, s20
	s_mov_b32 s40, 21
	s_mov_b32 s36, 14
	s_mov_b32 s34, 21
	s_cmpk_gt_i32 s26, 0x3fff
	s_cbranch_scc1 .LBB0_640
	s_ashr_i32 s43, s42, 31
	s_lshl_b64 s[42:43], s[42:43], 3
	s_add_u32 s42, s0, s42
	s_addc_u32 s43, s1, s43
	s_ashr_i32 s41, s40, 31
	s_lshl_b64 s[40:41], s[40:41], 3
	s_add_u32 s40, s0, s40
	s_addc_u32 s41, s1, s41
	s_ashr_i32 s37, s36, 31
	s_lshl_b64 s[36:37], s[36:37], 3
	s_add_u32 s36, s0, s36
	s_addc_u32 s37, s1, s37
	s_ashr_i32 s35, s34, 31
	s_lshl_b64 s[34:35], s[34:35], 3
	s_add_u32 s44, s0, s34
	s_addc_u32 s45, s1, s35
	s_load_dwordx2 s[34:35], s[42:43], 0x0
	s_nop 0
	s_load_dwordx2 s[36:37], s[36:37], 0x0
	s_nop 0
	s_load_dwordx2 s[44:45], s[44:45], 0x0
	s_nop 0
	s_load_dwordx2 s[42:43], s[40:41], 0x0
	v_readlane_b32 s20, v255, 30
	s_lshl_b32 s20, s20, 11
	s_lshl_b64 s[40:41], s[20:21], 2
	s_waitcnt lgkmcnt(0)
	s_add_u32 s46, s36, s40
	s_addc_u32 s47, s37, s41
	s_ashr_i32 s27, s26, 31
	s_lshl_b64 s[40:41], s[26:27], 12
	v_and_b32_e32 v10, 63, v0
	s_add_u32 s36, s42, s40
	v_lshlrev_b32_e32 v0, 4, v10
	s_addc_u32 s37, s43, s41
	v_lshl_add_u64 v[2:3], s[36:37], 0, v[0:1]
	s_mov_b64 s[48:49], 0x18e00000
	s_add_u32 s40, s34, s40
	s_mov_b32 s20, 0x18e00000
	v_lshl_add_u64 v[4:5], v[2:3], 0, s[48:49]
	s_addc_u32 s41, s35, s41
	v_add_co_u32_e32 v2, vcc, s20, v2
	v_lshl_add_u64 v[6:7], s[40:41], 0, v[0:1]
	s_nop 0
	v_addc_co_u32_e32 v3, vcc, 0, v3, vcc
	s_mov_b32 s20, 0x2d600000
	global_load_dwordx4 v[34:37], v[4:5], off offset:3072
	global_load_dwordx4 v[42:45], v[4:5], off offset:2048
	global_load_dwordx4 v[50:53], v[4:5], off offset:1024
	global_load_dwordx4 v[54:57], v[2:3], off
	v_add_co_u32_e32 v2, vcc, s20, v6
	s_mov_b64 s[40:41], 0x2d600000
	s_nop 0
	v_addc_co_u32_e32 v3, vcc, 0, v7, vcc
	v_lshl_add_u64 v[8:9], v[6:7], 0, s[40:41]
	global_load_dwordx4 v[62:65], v[2:3], off nt
	global_load_dwordx4 v[58:61], v[8:9], off offset:1024 nt
	global_load_dwordx4 v[46:49], v[8:9], off offset:2048 nt
	global_load_dwordx4 v[38:41], v[8:9], off offset:3072 nt
	v_and_b32_e32 v2, 64, v240
	v_mov_b32_e32 v3, v1
	v_add_u32_e32 v11, 64, v2
	v_lshlrev_b32_e32 v2, 5, v10
	v_lshl_add_u64 v[66:67], s[46:47], 0, v[2:3]
	s_mov_b64 s[46:47], 0x1000
	v_lshl_add_u64 v[68:69], v[66:67], 0, s[46:47]
	s_mov_b64 s[46:47], 0x1800
	v_lshl_add_u64 v[70:71], v[66:67], 0, s[46:47]
	global_load_dwordx4 v[128:131], v[66:67], off offset:16
	global_load_dwordx4 v[132:135], v[66:67], off
	global_load_dwordx4 v[136:139], v[66:67], off offset:2064
	global_load_dwordx4 v[140:143], v[66:67], off offset:2048
	global_load_dwordx4 v[144:147], v[68:69], off offset:16
	global_load_dwordx4 v[148:151], v[68:69], off
	global_load_dwordx4 v[152:155], v[70:71], off offset:16
	global_load_dwordx4 v[156:159], v[70:71], off
	s_waitcnt vmcnt(0)
	s_lshl_b64 s[46:47], s[26:27], 2
	v_xor_b32_e32 v4, 1, v240
	s_add_u32 s20, s44, s46
	v_xor_b32_e32 v5, 2, v240
	v_cmp_lt_i32_e32 vcc, v4, v11
	s_addc_u32 s23, s45, s47
	v_xor_b32_e32 v6, 4, v240
	v_cndmask_b32_e32 v4, v240, v4, vcc
	v_cmp_lt_i32_e32 vcc, v5, v11
	s_add_u32 s44, s20, 0x1c0000
	v_xor_b32_e32 v7, 8, v240
	v_cndmask_b32_e32 v5, v240, v5, vcc
	v_cmp_lt_i32_e32 vcc, v6, v11
	s_addc_u32 s45, s23, 0
	s_sub_i32 s20, s26, s22
	s_addk_i32 s20, 0x100
	s_and_b32 s26, s26, 0x7ff
	s_add_i32 s22, s20, s22
	v_xor_b32_e32 v8, 16, v240
	v_cndmask_b32_e32 v6, v240, v6, vcc
	v_cmp_lt_i32_e32 vcc, v7, v11
	s_ashr_i32 s23, s22, 31
	v_xor_b32_e32 v9, 32, v240
	v_cndmask_b32_e32 v7, v240, v7, vcc
	v_cmp_lt_i32_e32 vcc, v8, v11
	s_lshl_b64 s[22:23], s[22:23], 12
	s_add_u32 s46, s34, s22
	v_cndmask_b32_e32 v8, v240, v8, vcc
	v_cmp_lt_i32_e32 vcc, v9, v11
	s_addc_u32 s47, s35, s23
	v_cmp_eq_u32_e64 s[40:41], 0, v10
	v_cndmask_b32_e32 v9, v240, v9, vcc
	v_lshlrev_b32_e32 v116, 2, v4
	v_lshlrev_b32_e32 v117, 2, v5
	v_lshlrev_b32_e32 v118, 2, v6
	v_lshlrev_b32_e32 v119, 2, v7
	v_lshlrev_b32_e32 v120, 2, v8
	v_lshlrev_b32_e32 v121, 2, v9
	s_add_u32 s50, s42, s22
	s_addc_u32 s51, s43, s23
	s_waitcnt vmcnt(0)
	v_mov_b64_e32 v[18:19], v[42:43]
	v_mov_b64_e32 v[10:11], v[50:51]
	v_mov_b64_e32 v[2:3], v[54:55]
	v_mov_b64_e32 v[22:23], v[34:35]
	v_mov_b64_e32 v[4:5], v[56:57]
	v_mov_b64_e32 v[12:13], v[52:53]
	v_mov_b64_e32 v[6:7], v[62:63]
	v_mov_b64_e32 v[14:15], v[58:59]
	v_mov_b64_e32 v[26:27], v[46:47]
	v_mov_b64_e32 v[30:31], v[38:39]
	v_mov_b64_e32 v[20:21], v[44:45]
	v_mov_b64_e32 v[24:25], v[36:37]
	v_mov_b64_e32 v[8:9], v[64:65]
	v_mov_b64_e32 v[16:17], v[60:61]
	v_mov_b64_e32 v[28:29], v[48:49]
	v_mov_b64_e32 v[32:33], v[40:41]
	s_branch .LBB0_636
.LBB0_635:
	s_or_b64 exec, exec, s[34:35]
	s_movk_i32 s22, 0x400
	s_mov_b32 s23, 0
	s_add_u32 s44, s44, s22
	s_addc_u32 s45, s45, s23
	s_add_u32 s36, s36, 0x100000
	s_addc_u32 s37, s37, 0
	s_add_u32 s46, s46, 0x100000
	s_addc_u32 s47, s47, 0
	s_add_u32 s50, s50, 0x100000
	v_mov_b64_e32 v[56:57], v[4:5]
	v_mov_b64_e32 v[52:53], v[12:13]
	v_mov_b64_e32 v[44:45], v[20:21]
	s_waitcnt lgkmcnt(0)
	v_mov_b64_e32 v[36:37], v[24:25]
	v_mov_b64_e32 v[64:65], v[8:9]
	v_mov_b64_e32 v[60:61], v[16:17]
	v_mov_b64_e32 v[48:49], v[28:29]
	v_mov_b64_e32 v[40:41], v[32:33]
	s_addc_u32 s51, s51, 0
	s_andn2_b64 vcc, exec, s[52:53]
	v_mov_b64_e32 v[54:55], v[2:3]
	v_mov_b64_e32 v[50:51], v[10:11]
	v_mov_b64_e32 v[42:43], v[18:19]
	v_mov_b64_e32 v[34:35], v[22:23]
	v_mov_b64_e32 v[62:63], v[6:7]
	v_mov_b64_e32 v[58:59], v[14:15]
	v_mov_b64_e32 v[46:47], v[26:27]
	v_mov_b64_e32 v[38:39], v[30:31]
	s_cbranch_vccz .LBB0_640

; __device__ __forceinline__ unsigned xb_ld(unsigned* p)              { return __hip_atomic_load(p, __ATOMIC_RELAXED, __HIP_MEMORY_SCOPE_AGENT); }
; __device__ __forceinline__ unsigned xb_add(unsigned* p, unsigned v) { return __hip_atomic_fetch_add(p, v, __ATOMIC_RELAXED, __HIP_MEMORY_SCOPE_AGENT); }
; #define XB_SPIN(cond, bar) do { unsigned _sp = 0; while (cond) { __builtin_amdgcn_s_sleep(1); \
;     if ((++_sp & 255u) == 0u) { if (xb_ld(&(bar)[XB_TMO])) break; if (_sp > XB_SPIN_CAP) { atomicAdd(&(bar)[XB_TMO], 1u); break; } } } } while (0)
; __device__ __forceinline__ void xcd_barrier(const XcdBarrier& b) {
;     ...
;         const unsigned old = xb_add(&bar[XB_XSUB(b.x)], 1u);
;         const unsigned gen = old / nloc;
;         if (old + 1u == (gen + 1u) * nloc) {
;             __builtin_amdgcn_fence(__ATOMIC_RELEASE, "agent");
;             asm volatile("s_waitcnt vmcnt(0)" ::: "memory");
;             const unsigned og = xb_add(&bar[XB_TOP], 1u);
;             const unsigned tg = og / nx;
;             if (og + 1u == (tg + 1u) * nx) xb_add(&bar[XB_TOPGEN], 1u);
;             else XB_SPIN(xb_ld(&bar[XB_TOPGEN]) == tg, bar);
;             __builtin_amdgcn_fence(__ATOMIC_ACQUIRE, "agent");
;             xb_add(&bar[XB_XGEN(b.x)], 1u);
;             asm volatile("s_waitcnt vmcnt(0)" ::: "memory");
.Llseam_known_21747:
	s_cmp_eq_u32 s100, 1
	s_cbranch_scc0 .Llseam_full_21747
	v_readlane_b32 s22, v255, 30
	s_cmp_eq_u32 s22, 3
	s_cbranch_scc0 .LBB0_840
.Llseam_full_21747:
	buffer_wbl2 sc1
	s_waitcnt lgkmcnt(0)
	s_waitcnt vmcnt(0)
	v_mbcnt_lo_u32_b32 v0, s34, 0
	v_mbcnt_hi_u32_b32 v0, s35, v0
	v_cmp_eq_u32_e32 vcc, 0, v0
	s_and_saveexec_b64 s[36:37], vcc
	s_cbranch_execz .LBB0_826
	s_bcnt1_i32_b64 s22, s[34:35]
	v_mov_b32_e32 v3, s22
	v_readlane_b32 s22, v255, 6
	v_readlane_b32 s23, v255, 7
	s_nop 4
	global_atomic_add v3, v1, v3, s[22:23] sc0

; __device__ __forceinline__ const float* karg(int k) { int kk = k; asm volatile("" : "+s"(kk)); return ((const float* const __attribute__((address_space(4)))*)__builtin_amdgcn_kernarg_segment_ptr())[kk]; }
; #define PIN_TID() int tid = threadIdx.x; asm volatile("" : "+v"(tid)); const int lane = tid & 63, wid = __builtin_amdgcn_readfirstlane(tid >> 6), gw = blockIdx.x * NWAVES + wid; (void)lane; (void)gw
; template <bool FINAL, bool DUMMY = false> __device__ __forceinline__ void norm_rows(const bfu* F, bfu* XB, const float* g1, float* RS, float* xout, int gw, int NGW, int lane, bfu* dummy = nullptr) {
;     int m = gw; if (m >= M) return;
;     v4u fw[4], xw[4];
; #pragma unroll
;     for (int j = 0; j < 4; ++j) { fw[j] = __builtin_nontemporal_load((const v4u*)(F + (size_t)m * DM) + lane + 64 * j); xw[j] = ((const v4u*)(XB + (size_t)m * DM) + lane)[64 * j]; }
;     for (; m < M; m += NGW) {
;         f32x4 f[8], x[8]; float s = 0.f;
; #pragma unroll
;         for (int j = 0; j < 4; ++j) {
;             f[2 * j] = (f32x4){bflo(fw[j].x), bfhi(fw[j].x), bflo(fw[j].y), bfhi(fw[j].y)}; f[2 * j + 1] = (f32x4){bflo(fw[j].z), bfhi(fw[j].z), bflo(fw[j].w), bfhi(fw[j].w)};
;             x[2 * j] = (f32x4){bflo(xw[j].x), bfhi(xw[j].x), bflo(xw[j].y), bfhi(xw[j].y)}; x[2 * j + 1] = (f32x4){bflo(xw[j].z), bfhi(xw[j].z), bflo(xw[j].w), bfhi(xw[j].w)}; }
;         const int mn = m + NGW;
;         if (mn < M) {
; #pragma unroll
;             for (int j = 0; j < 4; ++j) { fw[j] = __builtin_nontemporal_load((const v4u*)(F + (size_t)mn * DM) + lane + 64 * j); xw[j] = ((const v4u*)(XB + (size_t)mn * DM) + lane)[64 * j]; }
; __global__ void __launch_bounds__(NTHR, 2) fwd(Args args) {
;     ...
;         if (XEN(9) && IN_PH()) for (int rep = 0; rep < XREP(9); ++rep) { PIN_TID(); if (XREP(9) > 1 && rep == 0) norm_rows<false, true>(F32, XN, karg(19) + l * DM, RS, nullptr, gw, NGW, lane, PROJ); else if (l + 1 < DEPTH) norm_rows<false>(F32, XN, karg(19) + l * DM, RS, nullptr, gw, NGW, lane); else norm_rows<true>(F32, XN, karg(19) + l * DM, nullptr, out, gw, NGW, lane); }
.LBB0_844:
	s_cmp_le_i32 s58, s20
	s_cselect_b64 s[4:5], -1, 0
	s_and_b64 s[22:23], s[4:5], s[26:27]
	s_andn2_b64 vcc, exec, s[22:23]
	s_cbranch_vccnz .LBB0_860
	v_mov_b32_e32 v0, v232
	s_mov_b64 s[34:35], -1
	v_readfirstlane_b32 s20, v0
	s_ashr_i32 s48, s20, 6
	s_and_b32 s20, s2, 7
	s_lshl_b32 s20, s20, 11
	s_lshr_b32 s27, s2, 3
	s_lshl_b32 s27, s27, 3
	s_add_i32 s20, s20, s27
	s_add_i32 s26, s48, s20
	v_readlane_b32 s20, v255, 30
	s_cmp_eq_u32 s20, 3
	v_and_b32_e32 v116, 63, v0
	s_cbranch_scc1 .LBB0_854
	s_mov_b32 s34, 21
	s_mov_b32 s40, 21
	s_mov_b32 s38, 19
	s_mov_b32 s36, 21
	s_cmpk_gt_i32 s26, 0x3fff
	s_cbranch_scc1 .LBB0_853
	s_ashr_i32 s35, s34, 31
	s_lshl_b64 s[22:23], s[34:35], 3
	s_add_u32 s22, s0, s22
	s_addc_u32 s23, s1, s23
	s_ashr_i32 s41, s40, 31
	s_load_dwordx2 s[34:35], s[22:23], 0x0
	s_lshl_b64 s[22:23], s[40:41], 3
	s_add_u32 s22, s0, s22
	s_addc_u32 s23, s1, s23
	s_ashr_i32 s39, s38, 31
	s_load_dwordx2 s[40:41], s[22:23], 0x0
	s_lshl_b64 s[22:23], s[38:39], 3
	s_add_u32 s22, s0, s22
	s_addc_u32 s23, s1, s23
	s_load_dwordx2 s[22:23], s[22:23], 0x0
	s_ashr_i32 s37, s36, 31
	s_lshl_b64 s[36:37], s[36:37], 3
	s_add_u32 s36, s0, s36
	v_readlane_b32 s20, v255, 30
	s_addc_u32 s37, s1, s37
	s_lshl_b32 s20, s20, 11
	s_load_dwordx2 s[42:43], s[36:37], 0x0
	s_lshl_b64 s[36:37], s[20:21], 2
	s_waitcnt lgkmcnt(0)
	s_add_u32 s44, s22, s36
	s_addc_u32 s45, s23, s37
	s_ashr_i32 s27, s26, 31
	s_lshl_b64 s[22:23], s[26:27], 12
	s_add_u32 s36, s40, s22
	s_addc_u32 s37, s41, s23
	v_lshlrev_b32_e32 v0, 4, v116
	s_add_u32 s22, s34, s22
	v_lshl_add_u64 v[2:3], s[36:37], 0, v[0:1]
	s_mov_b64 s[38:39], 0x18e00000
	s_addc_u32 s23, s35, s23
	s_mov_b32 s20, 0x18e00000
	v_lshl_add_u64 v[4:5], v[2:3], 0, s[38:39]
	v_lshl_add_u64 v[6:7], s[22:23], 0, v[0:1]
	s_mov_b64 s[22:23], 0x2d600000
	v_add_co_u32_e32 v2, vcc, s20, v2
	v_lshl_add_u64 v[8:9], v[6:7], 0, s[22:23]
	s_nop 0
	v_addc_co_u32_e32 v3, vcc, 0, v3, vcc
	s_mov_b32 s20, 0x2d600000
	global_load_dwordx4 v[34:37], v[4:5], off offset:3072
	global_load_dwordx4 v[38:41], v[8:9], off offset:3072 nt
	global_load_dwordx4 v[42:45], v[4:5], off offset:2048
	global_load_dwordx4 v[46:49], v[8:9], off offset:2048 nt
	global_load_dwordx4 v[50:53], v[4:5], off offset:1024
	global_load_dwordx4 v[54:57], v[8:9], off offset:1024 nt
	global_load_dwordx4 v[58:61], v[2:3], off
	v_add_co_u32_e32 v2, vcc, s20, v6
	s_mov_b64 s[22:23], 0x1000
	s_nop 0
	v_addc_co_u32_e32 v3, vcc, 0, v7, vcc
	global_load_dwordx4 v[62:65], v[2:3], off nt
	v_and_b32_e32 v2, 64, v240
	v_add_u32_e32 v2, 64, v2
	v_xor_b32_e32 v3, 1, v240
	v_cmp_lt_i32_e32 vcc, v3, v2
	v_cmp_eq_u32_e64 s[38:39], 0, v116
	s_waitcnt vmcnt(0)
	v_mov_b64_e32 v[30:31], v[38:39]
	v_cndmask_b32_e32 v3, v240, v3, vcc
	v_lshlrev_b32_e32 v117, 2, v3
	v_xor_b32_e32 v3, 2, v240
	v_cmp_lt_i32_e32 vcc, v3, v2
	v_mov_b64_e32 v[10:11], v[50:51]
	v_mov_b64_e32 v[18:19], v[42:43]
	v_cndmask_b32_e32 v3, v240, v3, vcc
	v_lshlrev_b32_e32 v118, 2, v3
	v_xor_b32_e32 v3, 4, v240
	v_cmp_lt_i32_e32 vcc, v3, v2
	v_mov_b64_e32 v[22:23], v[34:35]
	v_mov_b64_e32 v[6:7], v[62:63]
	v_cndmask_b32_e32 v3, v240, v3, vcc
	v_lshlrev_b32_e32 v119, 2, v3
	v_xor_b32_e32 v3, 8, v240
	v_cmp_lt_i32_e32 vcc, v3, v2
	v_mov_b64_e32 v[14:15], v[54:55]
	v_mov_b64_e32 v[26:27], v[46:47]
	v_cndmask_b32_e32 v3, v240, v3, vcc
	v_lshlrev_b32_e32 v120, 2, v3
	v_xor_b32_e32 v3, 16, v240
	v_cmp_lt_i32_e32 vcc, v3, v2
	v_mov_b64_e32 v[12:13], v[52:53]
	v_mov_b64_e32 v[20:21], v[44:45]
	v_cndmask_b32_e32 v3, v240, v3, vcc
	v_lshlrev_b32_e32 v121, 2, v3
	v_xor_b32_e32 v3, 32, v240
	v_cmp_lt_i32_e32 vcc, v3, v2
	v_mov_b64_e32 v[24:25], v[36:37]
	v_mov_b64_e32 v[8:9], v[64:65]
	v_cndmask_b32_e32 v2, v240, v3, vcc
	v_lshlrev_b32_e32 v122, 2, v2
	v_lshlrev_b32_e32 v2, 5, v116
	v_mov_b32_e32 v3, v1
	v_lshl_add_u64 v[66:67], s[44:45], 0, v[2:3]
	v_lshl_add_u64 v[68:69], v[66:67], 0, s[22:23]
	s_mov_b64 s[22:23], 0x1800
	v_lshl_add_u64 v[70:71], v[66:67], 0, s[22:23]
	global_load_dwordx4 v[128:131], v[66:67], off offset:16
	global_load_dwordx4 v[132:135], v[66:67], off
	global_load_dwordx4 v[136:139], v[66:67], off offset:2064
	global_load_dwordx4 v[140:143], v[66:67], off offset:2048
	global_load_dwordx4 v[144:147], v[68:69], off offset:16
	global_load_dwordx4 v[148:151], v[68:69], off
	global_load_dwordx4 v[152:155], v[70:71], off offset:16
	global_load_dwordx4 v[156:159], v[70:71], off
	s_waitcnt vmcnt(0)
	s_lshl_b64 s[22:23], s[26:27], 2
	s_add_u32 s20, s42, s22
	s_addc_u32 s22, s43, s23
	s_add_u32 s42, s20, 0x1c0000
	s_addc_u32 s43, s22, 0
	s_sub_i32 s20, s26, s48
	s_addk_i32 s20, 0x100
	s_add_i32 s22, s20, s48
	s_ashr_i32 s23, s22, 31
	s_lshl_b64 s[22:23], s[22:23], 12
	s_add_u32 s44, s34, s22
	s_addc_u32 s45, s35, s23
	s_add_u32 s46, s40, s22
	v_mov_b64_e32 v[2:3], v[58:59]
	s_addc_u32 s47, s41, s23
	s_and_b32 s20, s26, 0x7ff
	v_mov_b64_e32 v[4:5], v[60:61]
	v_mov_b64_e32 v[16:17], v[56:57]
	v_mov_b64_e32 v[28:29], v[48:49]
	v_mov_b64_e32 v[32:33], v[40:41]
	s_branch .LBB0_849
.LBB0_848:
	s_or_b64 exec, exec, s[34:35]
	s_movk_i32 s22, 0x400
	s_mov_b32 s23, 0
	s_add_u32 s42, s42, s22
	s_addc_u32 s43, s43, s23
	s_add_u32 s36, s36, 0x100000
	s_addc_u32 s37, s37, 0
	s_add_u32 s44, s44, 0x100000
	s_addc_u32 s45, s45, 0
	s_add_u32 s46, s46, 0x100000
	v_mov_b64_e32 v[60:61], v[4:5]
	v_mov_b64_e32 v[52:53], v[12:13]
	v_mov_b64_e32 v[44:45], v[20:21]
	s_waitcnt lgkmcnt(0)
	v_mov_b64_e32 v[36:37], v[24:25]
	v_mov_b64_e32 v[64:65], v[8:9]
	v_mov_b64_e32 v[56:57], v[16:17]
	v_mov_b64_e32 v[48:49], v[28:29]
	v_mov_b64_e32 v[40:41], v[32:33]
	s_addc_u32 s47, s47, 0
	s_and_b64 vcc, exec, s[50:51]
	v_mov_b64_e32 v[58:59], v[2:3]
	v_mov_b64_e32 v[50:51], v[10:11]
	v_mov_b64_e32 v[42:43], v[18:19]
	v_mov_b64_e32 v[34:35], v[22:23]
	v_mov_b64_e32 v[62:63], v[6:7]
	v_mov_b64_e32 v[54:55], v[14:15]
	v_mov_b64_e32 v[46:47], v[26:27]
	v_mov_b64_e32 v[38:39], v[30:31]
	s_cbranch_vccnz .LBB0_853

; __device__ __forceinline__ const float* karg(int k) { int kk = k; asm volatile("" : "+s"(kk)); return ((const float* const __attribute__((address_space(4)))*)__builtin_amdgcn_kernarg_segment_ptr())[kk]; }
; #define PIN_TID() int tid = threadIdx.x; asm volatile("" : "+v"(tid)); const int lane = tid & 63, wid = __builtin_amdgcn_readfirstlane(tid >> 6), gw = blockIdx.x * NWAVES + wid; (void)lane; (void)gw
; template <bool FINAL, bool DUMMY = false> __device__ __forceinline__ void norm_rows(const bfu* F, bfu* XB, const float* g1, float* RS, float* xout, int gw, int NGW, int lane, bfu* dummy = nullptr) {
;     int m = gw; if (m >= M) return;
;     v4u fw[4], xw[4];
; #pragma unroll
;     for (int j = 0; j < 4; ++j) { fw[j] = __builtin_nontemporal_load((const v4u*)(F + (size_t)m * DM) + lane + 64 * j); xw[j] = ((const v4u*)(XB + (size_t)m * DM) + lane)[64 * j]; }
;     for (; m < M; m += NGW) {
;         f32x4 f[8], x[8]; float s = 0.f;
; #pragma unroll
;         for (int j = 0; j < 4; ++j) {
;             f[2 * j] = (f32x4){bflo(fw[j].x), bfhi(fw[j].x), bflo(fw[j].y), bfhi(fw[j].y)}; f[2 * j + 1] = (f32x4){bflo(fw[j].z), bfhi(fw[j].z), bflo(fw[j].w), bfhi(fw[j].w)};
;             x[2 * j] = (f32x4){bflo(xw[j].x), bfhi(xw[j].x), bflo(xw[j].y), bfhi(xw[j].y)}; x[2 * j + 1] = (f32x4){bflo(xw[j].z), bfhi(xw[j].z), bflo(xw[j].w), bfhi(xw[j].w)}; }
;         const int mn = m + NGW;
;         if (mn < M) {
; #pragma unroll
;             for (int j = 0; j < 4; ++j) { fw[j] = __builtin_nontemporal_load((const v4u*)(F + (size_t)mn * DM) + lane + 64 * j); xw[j] = ((const v4u*)(XB + (size_t)mn * DM) + lane)[64 * j]; }
; __global__ void __launch_bounds__(NTHR, 2) fwd(Args args) {
;     ...
;         if (XEN(9) && IN_PH()) for (int rep = 0; rep < XREP(9); ++rep) { PIN_TID(); if (XREP(9) > 1 && rep == 0) norm_rows<false, true>(F32, XN, karg(19) + l * DM, RS, nullptr, gw, NGW, lane, PROJ); else if (l + 1 < DEPTH) norm_rows<false>(F32, XN, karg(19) + l * DM, RS, nullptr, gw, NGW, lane); else norm_rows<true>(F32, XN, karg(19) + l * DM, nullptr, out, gw, NGW, lane); }
.LBB0_854:
	s_andn2_b64 vcc, exec, s[34:35]
	s_cbranch_vccnz .LBB0_860
	v_readlane_b32 s20, v255, 25
	s_add_i32 s26, s48, s20
	s_mov_b32 s40, 21
	s_mov_b32 s38, 21
	s_mov_b32 s36, 19
	s_mov_b32 s34, 20
	s_cmpk_gt_i32 s26, 0x3fff
	s_cbranch_scc1 .LBB0_860
	s_ashr_i32 s41, s40, 31
	s_lshl_b64 s[22:23], s[40:41], 3
	s_add_u32 s22, s0, s22
	s_addc_u32 s23, s1, s23
	s_ashr_i32 s39, s38, 31
	s_lshl_b64 s[38:39], s[38:39], 3
	s_add_u32 s38, s0, s38
	s_addc_u32 s39, s1, s39
	s_ashr_i32 s37, s36, 31
	s_lshl_b64 s[36:37], s[36:37], 3
	s_add_u32 s40, s0, s36
	s_addc_u32 s41, s1, s37
	s_ashr_i32 s35, s34, 31
	s_lshl_b64 s[34:35], s[34:35], 3
	s_add_u32 s42, s0, s34
	s_addc_u32 s43, s1, s35
	s_load_dwordx2 s[34:35], s[22:23], 0x0
	s_load_dwordx2 s[36:37], s[38:39], 0x0
	s_nop 0
	s_load_dwordx2 s[22:23], s[40:41], 0x0
	s_load_dwordx2 s[38:39], s[42:43], 0x0
	s_ashr_i32 s27, s26, 31
	s_lshl_b64 s[40:41], s[26:27], 12
	s_waitcnt lgkmcnt(0)
	s_add_u32 s42, s36, s40
	s_addc_u32 s43, s37, s41
	v_lshlrev_b32_e32 v0, 4, v116
	v_lshl_add_u64 v[2:3], s[42:43], 0, v[0:1]
	s_mov_b64 s[42:43], 0x18e00000
	s_add_u32 s40, s34, s40
	s_mov_b32 s20, 0x18e00000
	v_lshl_add_u64 v[4:5], v[2:3], 0, s[42:43]
	s_addc_u32 s41, s35, s41
	v_add_co_u32_e32 v2, vcc, s20, v2
	v_lshl_add_u64 v[6:7], s[40:41], 0, v[0:1]
	s_nop 0
	v_addc_co_u32_e32 v3, vcc, 0, v3, vcc
	s_mov_b32 s20, 0x2d600000
	global_load_dwordx4 v[34:37], v[4:5], off offset:3072
	global_load_dwordx4 v[42:45], v[4:5], off offset:2048
	global_load_dwordx4 v[50:53], v[4:5], off offset:1024
	global_load_dwordx4 v[58:61], v[2:3], off
	v_add_co_u32_e32 v2, vcc, s20, v6
	s_mov_b64 s[40:41], 0x2d600000
	s_nop 0
	v_addc_co_u32_e32 v3, vcc, 0, v7, vcc
	v_lshl_add_u64 v[8:9], v[6:7], 0, s[40:41]
	global_load_dwordx4 v[62:65], v[2:3], off nt
	global_load_dwordx4 v[54:57], v[8:9], off offset:1024 nt
	global_load_dwordx4 v[46:49], v[8:9], off offset:2048 nt
	global_load_dwordx4 v[38:41], v[8:9], off offset:3072 nt
	v_and_b32_e32 v4, 64, v240
	v_xor_b32_e32 v5, 1, v240
	v_add_u32_e32 v4, 64, v4
	v_xor_b32_e32 v6, 2, v240
	v_cmp_lt_i32_e32 vcc, v5, v4
	v_xor_b32_e32 v7, 4, v240
	v_xor_b32_e32 v8, 8, v240
	v_cndmask_b32_e32 v5, v240, v5, vcc
	v_cmp_lt_i32_e32 vcc, v6, v4
	v_xor_b32_e32 v9, 16, v240
	v_xor_b32_e32 v10, 32, v240
	v_cndmask_b32_e32 v6, v240, v6, vcc
	v_cmp_lt_i32_e32 vcc, v7, v4
	v_lshlrev_b32_e32 v2, 5, v116
	v_mov_b32_e32 v3, v1
	v_cndmask_b32_e32 v7, v240, v7, vcc
	v_cmp_lt_i32_e32 vcc, v8, v4
	v_lshlrev_b32_e32 v91, 2, v5
	v_readlane_b32 s20, v255, 26
	v_cndmask_b32_e32 v8, v240, v8, vcc
	v_cmp_lt_i32_e32 vcc, v9, v4
	v_lshlrev_b32_e32 v124, 2, v6
	v_lshlrev_b32_e32 v125, 2, v7
	v_cndmask_b32_e32 v9, v240, v9, vcc
	v_cmp_lt_i32_e32 vcc, v10, v4
	v_lshlrev_b32_e32 v126, 2, v8
	v_lshlrev_b32_e32 v127, 2, v9
	v_cndmask_b32_e32 v4, v240, v10, vcc
	v_lshlrev_b32_e32 v128, 2, v4
	v_lshl_add_u64 v[4:5], s[22:23], 0, v[2:3]
	s_mov_b64 s[22:23], 0x6000
	v_lshl_add_u64 v[66:67], v[4:5], 0, s[22:23]
	s_mov_b64 s[22:23], 0x7000
	v_lshl_add_u64 v[68:69], v[4:5], 0, s[22:23]
	s_mov_b64 s[22:23], 0x7800
	v_lshl_add_u64 v[70:71], v[4:5], 0, s[22:23]
	s_lshl_b64 s[22:23], s[26:27], 13
	s_add_u32 s22, s38, s22
	s_addc_u32 s23, s39, s23
	s_add_i32 s38, s20, s48
	v_lshl_add_u64 v[2:3], s[22:23], 0, v[2:3]
	s_ashr_i32 s39, s38, 31
	s_mov_b64 s[22:23], 0x1000
	v_lshl_add_u64 v[72:73], v[2:3], 0, s[22:23]
	s_lshl_b64 s[22:23], s[38:39], 12
	s_add_u32 s36, s36, s22
	s_addc_u32 s37, s37, s23
	s_add_u32 s40, s34, s22
	s_addc_u32 s41, s35, s23
	s_waitcnt vmcnt(0)
	v_mov_b64_e32 v[18:19], v[42:43]
	v_mov_b64_e32 v[10:11], v[50:51]
	v_mov_b64_e32 v[2:3], v[58:59]
	v_mov_b64_e32 v[22:23], v[34:35]
	v_mov_b64_e32 v[4:5], v[60:61]
	v_mov_b64_e32 v[12:13], v[52:53]
	v_mov_b64_e32 v[6:7], v[62:63]
	v_mov_b64_e32 v[14:15], v[54:55]
	v_mov_b64_e32 v[26:27], v[46:47]
	v_mov_b64_e32 v[30:31], v[38:39]
	v_mov_b64_e32 v[20:21], v[44:45]
	v_mov_b64_e32 v[24:25], v[36:37]
	v_mov_b64_e32 v[8:9], v[64:65]
	v_mov_b64_e32 v[16:17], v[56:57]
	v_mov_b64_e32 v[28:29], v[48:49]
	v_mov_b64_e32 v[32:33], v[40:41]
	s_branch .LBB0_858

; __device__ __forceinline__ unsigned xb_ld(unsigned* p)              { return __hip_atomic_load(p, __ATOMIC_RELAXED, __HIP_MEMORY_SCOPE_AGENT); }
; __device__ __forceinline__ unsigned xb_add(unsigned* p, unsigned v) { return __hip_atomic_fetch_add(p, v, __ATOMIC_RELAXED, __HIP_MEMORY_SCOPE_AGENT); }
; #define XB_SPIN(cond, bar) do { unsigned _sp = 0; while (cond) { __builtin_amdgcn_s_sleep(1); \
;     if ((++_sp & 255u) == 0u) { if (xb_ld(&(bar)[XB_TMO])) break; if (_sp > XB_SPIN_CAP) { atomicAdd(&(bar)[XB_TMO], 1u); break; } } } } while (0)
; __device__ __forceinline__ void xcd_barrier(const XcdBarrier& b) {
;     ...
;         const unsigned old = xb_add(&bar[XB_XSUB(b.x)], 1u);
;         const unsigned gen = old / nloc;
;         if (old + 1u == (gen + 1u) * nloc) {
;             __builtin_amdgcn_fence(__ATOMIC_RELEASE, "agent");
;             asm volatile("s_waitcnt vmcnt(0)" ::: "memory");
;             const unsigned og = xb_add(&bar[XB_TOP], 1u);
;             const unsigned tg = og / nx;
;             if (og + 1u == (tg + 1u) * nx) xb_add(&bar[XB_TOPGEN], 1u);
;             else XB_SPIN(xb_ld(&bar[XB_TOPGEN]) == tg, bar);
;             __builtin_amdgcn_fence(__ATOMIC_ACQUIRE, "agent");
;             xb_add(&bar[XB_XGEN(b.x)], 1u);
.LBB0_893:
	s_andn2_saveexec_b64 s[22:23], s[26:27]
	s_cbranch_execz .LBB0_126
	s_mov_b64 s[26:27], exec
	s_cmp_lg_u32 s100, 0
	s_cbranch_scc1 .Llseam_known_23319
	v_readlane_b32 s22, v255, 6
	v_readlane_b32 s23, v255, 7
	s_nop 4
	global_load_dword v6, v1, s[22:23] offset:1024 sc1
	global_load_dword v7, v1, s[22:23] offset:1088 sc1
	global_load_dword v8, v1, s[22:23] offset:1152 sc1
	global_load_dword v9, v1, s[22:23] offset:1216 sc1
	global_load_dword v10, v1, s[22:23] offset:1280 sc1
	global_load_dword v11, v1, s[22:23] offset:1344 sc1
	global_load_dword v12, v1, s[22:23] offset:1408 sc1
	global_load_dword v13, v1, s[22:23] offset:1472 sc1
	s_waitcnt vmcnt(0)
	v_add_u32_e32 v14, -1, v6
	v_and_b32_e32 v14, v14, v6
	v_add_u32_e32 v15, -1, v7
	v_and_b32_e32 v15, v15, v7
	v_or_b32_e32 v14, v14, v15
	v_add_u32_e32 v15, -1, v8
	v_and_b32_e32 v15, v15, v8
	v_or_b32_e32 v14, v14, v15
	v_add_u32_e32 v15, -1, v9
	v_and_b32_e32 v15, v15, v9
	v_or_b32_e32 v14, v14, v15
	v_add_u32_e32 v15, -1, v10
	v_and_b32_e32 v15, v15, v10
	v_or_b32_e32 v14, v14, v15
	v_add_u32_e32 v15, -1, v11
	v_and_b32_e32 v15, v15, v11
	v_or_b32_e32 v14, v14, v15
	v_add_u32_e32 v15, -1, v12
	v_and_b32_e32 v15, v15, v12
	v_or_b32_e32 v14, v14, v15
	v_add_u32_e32 v15, -1, v13
	v_and_b32_e32 v15, v15, v13
	v_or_b32_e32 v14, v14, v15
	s_nop 0
	v_readfirstlane_b32 s22, v14
	s_cmp_eq_u32 s22, 0
	s_cselect_b32 s100, 1, 2
.Llseam_known_23319:
	s_cmp_eq_u32 s100, 1
	s_cbranch_scc1 .LBB0_910
	buffer_wbl2 sc1
	s_waitcnt lgkmcnt(0)
	s_waitcnt vmcnt(0)
	v_mbcnt_lo_u32_b32 v0, s26, 0
	v_mbcnt_hi_u32_b32 v0, s27, v0
	v_cmp_eq_u32_e32 vcc, 0, v0
	s_and_saveexec_b64 s[34:35], vcc
	s_cbranch_execz .LBB0_896
	s_bcnt1_i32_b64 s20, s[26:27]
	v_readlane_b32 s22, v255, 6
	v_mov_b32_e32 v3, s20
	v_readlane_b32 s23, v255, 7
	s_nop 4
	global_atomic_add v3, v1, v3, s[22:23] sc0

; __global__ void __launch_bounds__(NTHR, 2) fwd(Args args) {
	.amdhsa_kernel _Z3fwd4Args
		.amdhsa_group_segment_fixed_size 0
		.amdhsa_private_segment_fixed_size 0
		.amdhsa_kernarg_size 440
		.amdhsa_user_sgpr_count 2
		.amdhsa_user_sgpr_dispatch_ptr 0
		.amdhsa_user_sgpr_queue_ptr 0
		.amdhsa_user_sgpr_kernarg_segment_ptr 1
		.amdhsa_user_sgpr_dispatch_id 0
		.amdhsa_user_sgpr_kernarg_preload_length 0
		.amdhsa_user_sgpr_kernarg_preload_offset 0
		.amdhsa_user_sgpr_private_segment_size 0
		.amdhsa_uses_dynamic_stack 0
		.amdhsa_enable_private_segment 0
		.amdhsa_system_sgpr_workgroup_id_x 1
		.amdhsa_system_sgpr_workgroup_id_y 0
		.amdhsa_system_sgpr_workgroup_id_z 0
		.amdhsa_system_sgpr_workgroup_info 0
		.amdhsa_system_vgpr_workitem_id 2
		.amdhsa_next_free_vgpr 256
		.amdhsa_next_free_sgpr 102
		.amdhsa_accum_offset 256
		.amdhsa_reserve_vcc 1
		.amdhsa_float_round_mode_32 0
		.amdhsa_float_round_mode_16_64 0
		.amdhsa_float_denorm_mode_32 3
		.amdhsa_float_denorm_mode_16_64 3
		.amdhsa_dx10_clamp 1
		.amdhsa_ieee_mode 1
		.amdhsa_fp16_overflow 0
		.amdhsa_tg_split 0
		.amdhsa_exception_fp_ieee_invalid_op 0
		.amdhsa_exception_fp_denorm_src 0
		.amdhsa_exception_fp_ieee_div_zero 0
		.amdhsa_exception_fp_ieee_overflow 0
		.amdhsa_exception_fp_ieee_underflow 0
		.amdhsa_exception_fp_ieee_inexact 0
		.amdhsa_exception_int_div_zero 0
	.end_amdhsa_kernel

; __global__ void __launch_bounds__(NTHR, 2) fwd(Args args) {
amdhsa.kernels:
  - .agpr_count:     0
    .args:
      - .offset:         0
        .size:           184
        .value_kind:     by_value
      - .offset:         184
        .size:           4
        .value_kind:     hidden_block_count_x
      - .offset:         188
        .size:           4
        .value_kind:     hidden_block_count_y
      - .offset:         192
        .size:           4
        .value_kind:     hidden_block_count_z
      - .offset:         196
        .size:           2
        .value_kind:     hidden_group_size_x
      - .offset:         198
        .size:           2
        .value_kind:     hidden_group_size_y
      - .offset:         200
        .size:           2
        .value_kind:     hidden_group_size_z
      - .offset:         202
        .size:           2
        .value_kind:     hidden_remainder_x
      - .offset:         204
        .size:           2
        .value_kind:     hidden_remainder_y
      - .offset:         206
        .size:           2
        .value_kind:     hidden_remainder_z
      - .offset:         224
        .size:           8
        .value_kind:     hidden_global_offset_x
      - .offset:         232
        .size:           8
        .value_kind:     hidden_global_offset_y
      - .offset:         240
        .size:           8
        .value_kind:     hidden_global_offset_z
      - .offset:         248
        .size:           2
        .value_kind:     hidden_grid_dims
      - .offset:         272
        .size:           8
        .value_kind:     hidden_multigrid_sync_arg
      - .offset:         304
        .size:           4
        .value_kind:     hidden_dynamic_lds_size
    .group_segment_fixed_size: 0
    .kernarg_segment_align: 8
    .kernarg_segment_size: 440
    .language:       OpenCL C
    .language_version:
      - 2
      - 0
    .max_flat_workgroup_size: 512
    .name:           _Z3fwd4Args
    .private_segment_fixed_size: 0
    .sgpr_count:     108
    .sgpr_spill_count: 123
    .symbol:         _Z3fwd4Args.kd
    .uniform_work_group_size: 1
    .uses_dynamic_stack: false
    .vgpr_count:     256
    .vgpr_spill_count: 0
    .wavefront_size: 64
